# combination + attention per-unit gate-slice fill: first three pieces in flight together instead of a serialized load/wait/write loop
# baseline (speedup 1.0000x reference)
.LBB0_321:
	s_cmpk_gt_i32 s6, 0x1ff
	s_mov_b64 s[0:1], -1
	s_cbranch_scc1 .LBB0_320
	s_lshl_b32 s0, s6, 2
	s_add_i32 s0, s0, 0
	s_add_i32 s0, s0, 0x1e800
	v_mov_b32_e32 v0, s0
	ds_read_b32 v0, v0
	v_mov_b32_e32 v1, v252
	s_waitcnt lgkmcnt(0)
	v_readfirstlane_b32 s0, v0
	s_lshl_b32 s6, s0, 2
	s_add_i32 s6, s6, 0
	s_add_i32 s6, s6, 0x1e000
	v_mov_b32_e32 v0, s6
	ds_read_b32 v0, v0
	s_and_b32 s1, s0, 31
	s_lshl_b32 s6, s1, 2
	s_ashr_i32 s12, s0, 8
	v_readfirstlane_b32 s23, v1
	s_waitcnt lgkmcnt(0)
	v_sub_u32_e32 v0, s6, v0
	s_ashr_i32 s13, s12, 31
	v_readfirstlane_b32 s24, v0
	s_lshr_b32 s38, s23, 6
	s_lshl_b64 s[10:11], s[12:13], 13
	s_add_i32 s20, s24, 4
	s_lshl_b32 s25, s1, 8
	s_ashr_i32 s18, s0, 5
	s_lshl_b32 s0, s20, 6
	s_or_b32 s1, s10, s25
	s_lshl_b32 s39, s38, 5
	s_add_u32 s10, s1, s39
	s_addc_u32 s11, s11, 0
	s_lshl_b64 s[16:17], s[10:11], 10
	s_add_u32 s1, s3, s16
	s_addc_u32 s16, s26, s17
	s_lshl_b32 s17, s18, 6
	s_and_b32 s17, s17, 0x1c0
	s_lshl_b32 s37, s17, 1
	s_add_u32 s42, s1, s37
	s_addc_u32 s43, s16, 0
	s_ashr_i32 s21, s20, 31
	s_lshl_b64 s[16:17], s[20:21], 15
	s_lshl_b64 s[12:13], s[12:13], 22
	s_add_u32 s12, s16, s12
	s_addc_u32 s13, s17, s13
	s_lshl_b64 s[12:13], s[12:13], 1
	s_add_u32 s1, s27, s12
	s_addc_u32 s16, s28, s13
	s_add_u32 s1, s1, s37
	s_addc_u32 s16, s16, 0
	s_add_u32 s12, s29, s12
	s_addc_u32 s13, s30, s13
	s_add_u32 s17, s12, s37
	s_addc_u32 s19, s13, 0
	s_lshl_b32 s12, s38, 4
	s_add_u32 s12, s1, s12
	s_addc_u32 s13, s16, 0
	s_lshl_b32 s1, s23, 8
	s_and_b32 s1, s1, 0xc000
	s_add_u32 s1, s17, s1
	s_addc_u32 s17, s19, 0
	s_lshr_b32 s16, s23, 2
	s_and_b32 s16, s16, 0x3fffffc0
	s_add_u32 s16, s1, s16
	s_addc_u32 s17, s17, 0
	s_lshl_b32 s22, s38, 10
	s_cmp_lg_u32 0, -1
	s_cselect_b32 s1, 0, 0
	s_add_i32 s40, s22, s1
	s_add_i32 s1, s25, 0x100
	s_add_i32 s41, s40, 0x6000
	s_lshr_b32 s1, s1, 6
	s_mov_b32 s19, m0
	s_mov_b32 m0, s40
	s_nop 0
	global_load_lds_dwordx4 v211, s[12:13]
	s_mov_b32 m0, s19
	s_add_u32 s44, s12, 0x10000
	s_mov_b32 s19, m0
	s_mov_b32 m0, s41
	s_nop 0
	global_load_lds_dwordx4 v212, s[16:17]
	s_mov_b32 m0, s19
	s_addc_u32 s45, s13, 0
	s_add_i32 s19, s40, 0x2000
	s_mov_b32 s21, m0
	s_mov_b32 m0, s19
	s_nop 0
	global_load_lds_dwordx4 v211, s[44:45]
	s_mov_b32 m0, s21
	global_load_dwordx4 v[126:129], v253, s[42:43]
	global_load_dwordx4 v[122:125], v253, s[42:43] offset:32
	global_load_dwordx4 v[118:121], v253, s[42:43] offset:64
	global_load_dwordx4 v[114:117], v253, s[42:43] offset:96
	s_sub_i32 s42, s1, s20
	s_add_u32 s20, s12, 0x20000
	s_addc_u32 s21, s13, 0
	s_add_i32 s1, s40, 0x4000
	s_mov_b32 s19, m0
	s_mov_b32 m0, s1
	s_nop 0
	global_load_lds_dwordx4 v211, s[20:21]
	s_mov_b32 m0, s19
	s_lshl_b32 s43, s42, 4
	v_cmp_gt_i32_e32 vcc, s43, v1
	s_and_saveexec_b64 s[20:21], vcc
	s_cbranch_execz .LBB0_325
	s_ashr_i32 s19, s18, 31
	s_ashr_i32 s1, s0, 31
	s_lshl_b64 s[18:19], s[18:19], 15
	s_lshl_b64 s[44:45], s[0:1], 2
	s_add_u32 s18, s18, s44
	s_addc_u32 s19, s19, s45
	v_lshl_add_u32 v2, s24, 8, v251
	v_lshl_add_u64 v[0:1], v[196:197], 0, s[18:19]
	s_mov_b64 s[18:19], 0
	v_mov_b32_e32 v3, v252
	s_mov_b64 s[44:45], exec
	global_load_dwordx4 v[4:7], v[0:1], off
	v_add_u32_e32 v3, 0x200, v3
	v_lshl_add_u64 v[0:1], v[0:1], 0, s[8:9]
	v_cmp_gt_i32_e32 vcc, s43, v3
	s_and_b64 exec, exec, vcc
	s_mov_b64 s[18:19], exec
	global_load_dwordx4 v[8:11], v[0:1], off
	v_add_u32_e32 v3, 0x200, v3
	v_lshl_add_u64 v[0:1], v[0:1], 0, s[8:9]
	v_cmp_gt_i32_e32 vcc, s43, v3
	s_and_b64 exec, exec, vcc
	global_load_dwordx4 v[12:15], v[0:1], off
	v_add_u32_e32 v3, 0x200, v3
	v_lshl_add_u64 v[0:1], v[0:1], 0, s[8:9]
	s_waitcnt vmcnt(0)
	ds_write_b128 v2, v[12:15] offset:16384
	v_add_u32_e32 v16, 0x6000, v2
	v_cmp_gt_i32_e32 vcc, s43, v3
	s_mov_b64 exec, s[18:19]
	ds_write_b128 v2, v[8:11] offset:8192
	s_mov_b64 exec, s[44:45]
	ds_write_b128 v2, v[4:7]
	s_mov_b64 s[18:19], 0
	s_mov_b64 exec, vcc
	v_mov_b32_e32 v2, v16
	s_cbranch_execz .LBB0_325
